# hand-written residual (mode-1) GEMM epilogue: all x loads of the 4 row pairs issued before any store, counted vmcnt never waits on a store
# baseline (speedup 1.0000x reference)
.LBB0_540:
	s_andn2_b64 vcc, exec, s[10:11]
	s_cbranch_vccnz .LBB0_514
	v_lshl_or_b32 v129, s25, 8, v187
	v_lshlrev_b64 v[136:137], 12, v[162:163]
	v_lshl_add_u64 v[136:137], s[16:17], 0, v[136:137]
	v_lshlrev_b32_e32 v138, 2, v129
	v_mov_b32_e32 v139, 0
	v_lshl_add_u64 v[136:137], v[136:137], 0, v[138:139]
	v_lshlrev_b64 v[142:143], 11, v[162:163]
	v_lshl_add_u64 v[142:143], s[70:71], 0, v[142:143]
	v_lshlrev_b32_e32 v138, 1, v129
	v_lshl_add_u64 v[142:143], v[142:143], 0, v[138:139]
	s_lshl_b32 s10, s25, 2
	s_or_b32 s10, s10, s23
	s_lshl_b32 s10, s10, 2
	s_mov_b32 s11, 0
	v_lshlrev_b64 v[164:165], 6, v[162:163]
	v_lshl_add_u64 v[164:165], s[38:39], 0, v[164:165]
	v_lshl_add_u64 v[164:165], v[164:165], 0, s[10:11]
	v_mov_b32_e32 v140, v136
	v_mov_b32_e32 v141, v137
	s_mov_b64 s[10:11], 0x10000
	s_mov_b64 s[84:85], 0x50000
	s_mov_b64 s[100:101], 0x8000
	s_mov_b64 s[98:99], 0x28000
	v_lshl_add_u64 v[166:167], v[136:137], 0, s[10:11]
	global_load_dwordx4 v[190:193], v[136:137], off
	global_load_dwordx4 v[194:197], v[136:137], off offset:64
	global_load_dwordx4 v[198:201], v[136:137], off offset:512
	global_load_dwordx4 v[202:205], v[136:137], off offset:576
	global_load_dwordx4 v[206:209], v[166:167], off
	global_load_dwordx4 v[210:213], v[166:167], off offset:64
	global_load_dwordx4 v[214:217], v[166:167], off offset:512
	global_load_dwordx4 v[218:221], v[166:167], off offset:576
	v_lshl_add_u64 v[136:137], v[166:167], 0, s[10:11]
	v_lshl_add_u64 v[166:167], v[136:137], 0, s[10:11]
	global_load_dwordx4 v[222:225], v[136:137], off
	global_load_dwordx4 v[226:229], v[136:137], off offset:64
	global_load_dwordx4 v[230:233], v[136:137], off offset:512
	global_load_dwordx4 v[234:237], v[136:137], off offset:576
	global_load_dwordx4 v[238:241], v[166:167], off
	global_load_dwordx4 v[242:245], v[166:167], off offset:64
	global_load_dwordx4 v[246:249], v[166:167], off offset:512
	global_load_dwordx4 v[250:253], v[166:167], off offset:576
	v_lshl_add_u64 v[136:137], v[166:167], 0, s[84:85]
	s_waitcnt vmcnt(8)
	v_pk_fma_f32 v[124:125], s[82:83], v[124:125], v[190:191]
	v_pk_fma_f32 v[126:127], s[82:83], v[126:127], v[192:193]
	v_pk_fma_f32 v[116:117], s[82:83], v[116:117], v[194:195]
	v_pk_fma_f32 v[118:119], s[82:83], v[118:119], v[196:197]
	v_pk_fma_f32 v[108:109], s[82:83], v[108:109], v[198:199]
	v_pk_fma_f32 v[110:111], s[82:83], v[110:111], v[200:201]
	v_pk_fma_f32 v[100:101], s[82:83], v[100:101], v[202:203]
	v_pk_fma_f32 v[102:103], s[82:83], v[102:103], v[204:205]
	v_pk_fma_f32 v[120:121], s[82:83], v[120:121], v[206:207]
	v_pk_fma_f32 v[122:123], s[82:83], v[122:123], v[208:209]
	v_pk_fma_f32 v[112:113], s[82:83], v[112:113], v[210:211]
	v_pk_fma_f32 v[114:115], s[82:83], v[114:115], v[212:213]
	v_pk_fma_f32 v[104:105], s[82:83], v[104:105], v[214:215]
	v_pk_fma_f32 v[106:107], s[82:83], v[106:107], v[216:217]
	v_pk_fma_f32 v[96:97], s[82:83], v[96:97], v[218:219]
	v_pk_fma_f32 v[98:99], s[82:83], v[98:99], v[220:221]
	v_lshl_add_u64 v[166:167], v[136:137], 0, s[10:11]
	global_load_dwordx4 v[190:193], v[136:137], off
	global_load_dwordx4 v[194:197], v[136:137], off offset:64
	global_load_dwordx4 v[198:201], v[136:137], off offset:512
	global_load_dwordx4 v[202:205], v[136:137], off offset:576
	global_load_dwordx4 v[206:209], v[166:167], off
	global_load_dwordx4 v[210:213], v[166:167], off offset:64
	global_load_dwordx4 v[214:217], v[166:167], off offset:512
	global_load_dwordx4 v[218:221], v[166:167], off offset:576
	v_lshl_add_u64 v[136:137], v[166:167], 0, s[10:11]
	s_waitcnt vmcnt(8)
	v_pk_fma_f32 v[92:93], s[82:83], v[92:93], v[222:223]
	v_pk_fma_f32 v[94:95], s[82:83], v[94:95], v[224:225]
	v_pk_fma_f32 v[84:85], s[82:83], v[84:85], v[226:227]
	v_pk_fma_f32 v[86:87], s[82:83], v[86:87], v[228:229]
	v_pk_fma_f32 v[76:77], s[82:83], v[76:77], v[230:231]
	v_pk_fma_f32 v[78:79], s[82:83], v[78:79], v[232:233]
	v_pk_fma_f32 v[68:69], s[82:83], v[68:69], v[234:235]
	v_pk_fma_f32 v[70:71], s[82:83], v[70:71], v[236:237]
	v_pk_fma_f32 v[88:89], s[82:83], v[88:89], v[238:239]
	v_pk_fma_f32 v[90:91], s[82:83], v[90:91], v[240:241]
	v_pk_fma_f32 v[80:81], s[82:83], v[80:81], v[242:243]
	v_pk_fma_f32 v[82:83], s[82:83], v[82:83], v[244:245]
	v_pk_fma_f32 v[72:73], s[82:83], v[72:73], v[246:247]
	v_pk_fma_f32 v[74:75], s[82:83], v[74:75], v[248:249]
	v_pk_fma_f32 v[64:65], s[82:83], v[64:65], v[250:251]
	v_pk_fma_f32 v[66:67], s[82:83], v[66:67], v[252:253]
	v_lshl_add_u64 v[166:167], v[136:137], 0, s[10:11]
	global_load_dwordx4 v[222:225], v[136:137], off
	global_load_dwordx4 v[226:229], v[136:137], off offset:64
	global_load_dwordx4 v[230:233], v[136:137], off offset:512
	global_load_dwordx4 v[234:237], v[136:137], off offset:576
	global_load_dwordx4 v[238:241], v[166:167], off
	global_load_dwordx4 v[242:245], v[166:167], off offset:64
	global_load_dwordx4 v[246:249], v[166:167], off offset:512
	global_load_dwordx4 v[250:253], v[166:167], off offset:576
	v_lshl_add_u64 v[174:175], v[140:141], 0, s[10:11]
	v_lshl_add_u64 v[138:139], v[142:143], 0, s[100:101]
	global_store_dwordx4 v[140:141], v[124:127], off
	v_cvt_pk_bf16_f32 v128, v124, v125
	v_cvt_pk_bf16_f32 v129, v126, v127
	v_mul_f32_e32 v148, v124, v124
	v_fmac_f32_e32 v148, v125, v125
	v_fmac_f32_e32 v148, v126, v126
	v_fmac_f32_e32 v148, v127, v127
	global_store_dwordx2 v[142:143], v[128:129], off
	global_store_dwordx4 v[140:141], v[116:119], off offset:64
	v_cvt_pk_bf16_f32 v130, v116, v117
	v_cvt_pk_bf16_f32 v131, v118, v119
	v_fmac_f32_e32 v148, v116, v116
	v_fmac_f32_e32 v148, v117, v117
	v_fmac_f32_e32 v148, v118, v118
	v_fmac_f32_e32 v148, v119, v119
	global_store_dwordx2 v[142:143], v[130:131], off offset:32
	global_store_dwordx4 v[140:141], v[108:111], off offset:512
	v_cvt_pk_bf16_f32 v132, v108, v109
	v_cvt_pk_bf16_f32 v133, v110, v111
	v_fmac_f32_e32 v148, v108, v108
	v_fmac_f32_e32 v148, v109, v109
	v_fmac_f32_e32 v148, v110, v110
	v_fmac_f32_e32 v148, v111, v111
	global_store_dwordx2 v[142:143], v[132:133], off offset:256
	global_store_dwordx4 v[140:141], v[100:103], off offset:576
	v_cvt_pk_bf16_f32 v134, v100, v101
	v_cvt_pk_bf16_f32 v135, v102, v103
	v_fmac_f32_e32 v148, v100, v100
	v_fmac_f32_e32 v148, v101, v101
	v_fmac_f32_e32 v148, v102, v102
	v_fmac_f32_e32 v148, v103, v103
	global_store_dwordx2 v[142:143], v[134:135], off offset:288
	global_store_dwordx4 v[174:175], v[120:123], off
	v_cvt_pk_bf16_f32 v128, v120, v121
	v_cvt_pk_bf16_f32 v129, v122, v123
	v_mul_f32_e32 v173, v120, v120
	v_fmac_f32_e32 v173, v121, v121
	v_fmac_f32_e32 v173, v122, v122
	v_fmac_f32_e32 v173, v123, v123
	global_store_dwordx2 v[138:139], v[128:129], off
	global_store_dwordx4 v[174:175], v[112:115], off offset:64
	v_cvt_pk_bf16_f32 v130, v112, v113
	v_cvt_pk_bf16_f32 v131, v114, v115
	v_fmac_f32_e32 v173, v112, v112
	v_fmac_f32_e32 v173, v113, v113
	v_fmac_f32_e32 v173, v114, v114
	v_fmac_f32_e32 v173, v115, v115
	global_store_dwordx2 v[138:139], v[130:131], off offset:32
	global_store_dwordx4 v[174:175], v[104:107], off offset:512
	v_cvt_pk_bf16_f32 v132, v104, v105
	v_cvt_pk_bf16_f32 v133, v106, v107
	v_fmac_f32_e32 v173, v104, v104
	v_fmac_f32_e32 v173, v105, v105
	v_fmac_f32_e32 v173, v106, v106
	v_fmac_f32_e32 v173, v107, v107
	global_store_dwordx2 v[138:139], v[132:133], off offset:256
	global_store_dwordx4 v[174:175], v[96:99], off offset:576
	v_cvt_pk_bf16_f32 v134, v96, v97
	v_cvt_pk_bf16_f32 v135, v98, v99
	v_fmac_f32_e32 v173, v96, v96
	v_fmac_f32_e32 v173, v97, v97
	v_fmac_f32_e32 v173, v98, v98
	v_fmac_f32_e32 v173, v99, v99
	global_store_dwordx2 v[138:139], v[134:135], off offset:288
	v_mov_b32_e32 v177, v148
	v_mov_b32_e32 v181, v173
	s_nop 1
	v_permlane16_swap_b32_e32 v148, v177
	v_permlane16_swap_b32_e32 v173, v181
	v_add_f32_e32 v148, v148, v177
	v_add_f32_e32 v173, v173, v181
	v_mov_b32_e32 v177, v148
	v_mov_b32_e32 v181, v173
	s_nop 1
	v_permlane32_swap_b32_e32 v148, v177
	v_permlane32_swap_b32_e32 v173, v181
	v_add_f32_e32 v148, v148, v177
	v_add_f32_e32 v173, v173, v181
	s_and_saveexec_b64 s[78:79], s[6:7]
	global_store_dword v[164:165], v148, off
	global_store_dword v[164:165], v173, off offset:1024
	s_mov_b64 exec, s[78:79]
	v_lshl_add_u64 v[140:141], v[174:175], 0, s[10:11]
	v_lshl_add_u64 v[142:143], v[138:139], 0, s[100:101]
	v_lshl_add_u64 v[174:175], v[140:141], 0, s[10:11]
	v_lshl_add_u64 v[138:139], v[142:143], 0, s[100:101]
	global_store_dwordx4 v[140:141], v[92:95], off
	v_cvt_pk_bf16_f32 v128, v92, v93
	v_cvt_pk_bf16_f32 v129, v94, v95
	v_mul_f32_e32 v148, v92, v92
	v_fmac_f32_e32 v148, v93, v93
	v_fmac_f32_e32 v148, v94, v94
	v_fmac_f32_e32 v148, v95, v95
	global_store_dwordx2 v[142:143], v[128:129], off
	global_store_dwordx4 v[140:141], v[84:87], off offset:64
	v_cvt_pk_bf16_f32 v130, v84, v85
	v_cvt_pk_bf16_f32 v131, v86, v87
	v_fmac_f32_e32 v148, v84, v84
	v_fmac_f32_e32 v148, v85, v85
	v_fmac_f32_e32 v148, v86, v86
	v_fmac_f32_e32 v148, v87, v87
	global_store_dwordx2 v[142:143], v[130:131], off offset:32
	global_store_dwordx4 v[140:141], v[76:79], off offset:512
	v_cvt_pk_bf16_f32 v132, v76, v77
	v_cvt_pk_bf16_f32 v133, v78, v79
	v_fmac_f32_e32 v148, v76, v76
	v_fmac_f32_e32 v148, v77, v77
	v_fmac_f32_e32 v148, v78, v78
	v_fmac_f32_e32 v148, v79, v79
	global_store_dwordx2 v[142:143], v[132:133], off offset:256
	global_store_dwordx4 v[140:141], v[68:71], off offset:576
	v_cvt_pk_bf16_f32 v134, v68, v69
	v_cvt_pk_bf16_f32 v135, v70, v71
	v_fmac_f32_e32 v148, v68, v68
	v_fmac_f32_e32 v148, v69, v69
	v_fmac_f32_e32 v148, v70, v70
	v_fmac_f32_e32 v148, v71, v71
	global_store_dwordx2 v[142:143], v[134:135], off offset:288
	global_store_dwordx4 v[174:175], v[88:91], off
	v_cvt_pk_bf16_f32 v128, v88, v89
	v_cvt_pk_bf16_f32 v129, v90, v91
	v_mul_f32_e32 v173, v88, v88
	v_fmac_f32_e32 v173, v89, v89
	v_fmac_f32_e32 v173, v90, v90
	v_fmac_f32_e32 v173, v91, v91
	global_store_dwordx2 v[138:139], v[128:129], off
	global_store_dwordx4 v[174:175], v[80:83], off offset:64
	v_cvt_pk_bf16_f32 v130, v80, v81
	v_cvt_pk_bf16_f32 v131, v82, v83
	v_fmac_f32_e32 v173, v80, v80
	v_fmac_f32_e32 v173, v81, v81
	v_fmac_f32_e32 v173, v82, v82
	v_fmac_f32_e32 v173, v83, v83
	global_store_dwordx2 v[138:139], v[130:131], off offset:32
	global_store_dwordx4 v[174:175], v[72:75], off offset:512
	v_cvt_pk_bf16_f32 v132, v72, v73
	v_cvt_pk_bf16_f32 v133, v74, v75
	v_fmac_f32_e32 v173, v72, v72
	v_fmac_f32_e32 v173, v73, v73
	v_fmac_f32_e32 v173, v74, v74
	v_fmac_f32_e32 v173, v75, v75
	global_store_dwordx2 v[138:139], v[132:133], off offset:256
	global_store_dwordx4 v[174:175], v[64:67], off offset:576
	v_cvt_pk_bf16_f32 v134, v64, v65
	v_cvt_pk_bf16_f32 v135, v66, v67
	v_fmac_f32_e32 v173, v64, v64
	v_fmac_f32_e32 v173, v65, v65
	v_fmac_f32_e32 v173, v66, v66
	v_fmac_f32_e32 v173, v67, v67
	global_store_dwordx2 v[138:139], v[134:135], off offset:288
	v_mov_b32_e32 v177, v148
	v_mov_b32_e32 v181, v173
	s_nop 1
	v_permlane16_swap_b32_e32 v148, v177
	v_permlane16_swap_b32_e32 v173, v181
	v_add_f32_e32 v148, v148, v177
	v_add_f32_e32 v173, v173, v181
	v_mov_b32_e32 v177, v148
	v_mov_b32_e32 v181, v173
	s_nop 1
	v_permlane32_swap_b32_e32 v148, v177
	v_permlane32_swap_b32_e32 v173, v181
	v_add_f32_e32 v148, v148, v177
	v_add_f32_e32 v173, v173, v181
	s_and_saveexec_b64 s[78:79], s[6:7]
	global_store_dword v[164:165], v148, off offset:2048
	global_store_dword v[164:165], v173, off offset:3072
	s_mov_b64 exec, s[78:79]
	v_lshl_add_u64 v[140:141], v[174:175], 0, s[84:85]
	v_lshl_add_u64 v[142:143], v[138:139], 0, s[98:99]
	v_add_co_u32_e32 v164, vcc, 0x2000, v164
	s_nop 1
	v_addc_co_u32_e32 v165, vcc, 0, v165, vcc
	s_waitcnt vmcnt(44)
	v_pk_fma_f32 v[60:61], s[82:83], v[60:61], v[190:191]
	v_pk_fma_f32 v[62:63], s[82:83], v[62:63], v[192:193]
	v_pk_fma_f32 v[56:57], s[82:83], v[56:57], v[194:195]
	v_pk_fma_f32 v[58:59], s[82:83], v[58:59], v[196:197]
	v_pk_fma_f32 v[44:45], s[82:83], v[44:45], v[198:199]
	v_pk_fma_f32 v[46:47], s[82:83], v[46:47], v[200:201]
	v_pk_fma_f32 v[36:37], s[82:83], v[36:37], v[202:203]
	v_pk_fma_f32 v[38:39], s[82:83], v[38:39], v[204:205]
	v_pk_fma_f32 v[52:53], s[82:83], v[52:53], v[206:207]
	v_pk_fma_f32 v[54:55], s[82:83], v[54:55], v[208:209]
	v_pk_fma_f32 v[48:49], s[82:83], v[48:49], v[210:211]
	v_pk_fma_f32 v[50:51], s[82:83], v[50:51], v[212:213]
	v_pk_fma_f32 v[40:41], s[82:83], v[40:41], v[214:215]
	v_pk_fma_f32 v[42:43], s[82:83], v[42:43], v[216:217]
	v_pk_fma_f32 v[32:33], s[82:83], v[32:33], v[218:219]
	v_pk_fma_f32 v[34:35], s[82:83], v[34:35], v[220:221]
	v_lshl_add_u64 v[174:175], v[140:141], 0, s[10:11]
	v_lshl_add_u64 v[138:139], v[142:143], 0, s[100:101]
	global_store_dwordx4 v[140:141], v[60:63], off
	v_cvt_pk_bf16_f32 v128, v60, v61
	v_cvt_pk_bf16_f32 v129, v62, v63
	v_mul_f32_e32 v148, v60, v60
	v_fmac_f32_e32 v148, v61, v61
	v_fmac_f32_e32 v148, v62, v62
	v_fmac_f32_e32 v148, v63, v63
	global_store_dwordx2 v[142:143], v[128:129], off
	global_store_dwordx4 v[140:141], v[56:59], off offset:64
	v_cvt_pk_bf16_f32 v130, v56, v57
	v_cvt_pk_bf16_f32 v131, v58, v59
	v_fmac_f32_e32 v148, v56, v56
	v_fmac_f32_e32 v148, v57, v57
	v_fmac_f32_e32 v148, v58, v58
	v_fmac_f32_e32 v148, v59, v59
	global_store_dwordx2 v[142:143], v[130:131], off offset:32
	global_store_dwordx4 v[140:141], v[44:47], off offset:512
	v_cvt_pk_bf16_f32 v132, v44, v45
	v_cvt_pk_bf16_f32 v133, v46, v47
	v_fmac_f32_e32 v148, v44, v44
	v_fmac_f32_e32 v148, v45, v45
	v_fmac_f32_e32 v148, v46, v46
	v_fmac_f32_e32 v148, v47, v47
	global_store_dwordx2 v[142:143], v[132:133], off offset:256
	global_store_dwordx4 v[140:141], v[36:39], off offset:576
	v_cvt_pk_bf16_f32 v134, v36, v37
	v_cvt_pk_bf16_f32 v135, v38, v39
	v_fmac_f32_e32 v148, v36, v36
	v_fmac_f32_e32 v148, v37, v37
	v_fmac_f32_e32 v148, v38, v38
	v_fmac_f32_e32 v148, v39, v39
	global_store_dwordx2 v[142:143], v[134:135], off offset:288
	global_store_dwordx4 v[174:175], v[52:55], off
	v_cvt_pk_bf16_f32 v128, v52, v53
	v_cvt_pk_bf16_f32 v129, v54, v55
	v_mul_f32_e32 v173, v52, v52
	v_fmac_f32_e32 v173, v53, v53
	v_fmac_f32_e32 v173, v54, v54
	v_fmac_f32_e32 v173, v55, v55
	global_store_dwordx2 v[138:139], v[128:129], off
	global_store_dwordx4 v[174:175], v[48:51], off offset:64
	v_cvt_pk_bf16_f32 v130, v48, v49
	v_cvt_pk_bf16_f32 v131, v50, v51
	v_fmac_f32_e32 v173, v48, v48
	v_fmac_f32_e32 v173, v49, v49
	v_fmac_f32_e32 v173, v50, v50
	v_fmac_f32_e32 v173, v51, v51
	global_store_dwordx2 v[138:139], v[130:131], off offset:32
	global_store_dwordx4 v[174:175], v[40:43], off offset:512
	v_cvt_pk_bf16_f32 v132, v40, v41
	v_cvt_pk_bf16_f32 v133, v42, v43
	v_fmac_f32_e32 v173, v40, v40
	v_fmac_f32_e32 v173, v41, v41
	v_fmac_f32_e32 v173, v42, v42
	v_fmac_f32_e32 v173, v43, v43
	global_store_dwordx2 v[138:139], v[132:133], off offset:256
	global_store_dwordx4 v[174:175], v[32:35], off offset:576
	v_cvt_pk_bf16_f32 v134, v32, v33
	v_cvt_pk_bf16_f32 v135, v34, v35
	v_fmac_f32_e32 v173, v32, v32
	v_fmac_f32_e32 v173, v33, v33
	v_fmac_f32_e32 v173, v34, v34
	v_fmac_f32_e32 v173, v35, v35
	global_store_dwordx2 v[138:139], v[134:135], off offset:288
	v_mov_b32_e32 v177, v148
	v_mov_b32_e32 v181, v173
	s_nop 1
	v_permlane16_swap_b32_e32 v148, v177
	v_permlane16_swap_b32_e32 v173, v181
	v_add_f32_e32 v148, v148, v177
	v_add_f32_e32 v173, v173, v181
	v_mov_b32_e32 v177, v148
	v_mov_b32_e32 v181, v173
	s_nop 1
	v_permlane32_swap_b32_e32 v148, v177
	v_permlane32_swap_b32_e32 v173, v181
	v_add_f32_e32 v148, v148, v177
	v_add_f32_e32 v173, v173, v181
	s_and_saveexec_b64 s[78:79], s[6:7]
	global_store_dword v[164:165], v148, off
	global_store_dword v[164:165], v173, off offset:1024
	s_mov_b64 exec, s[78:79]
	v_lshl_add_u64 v[140:141], v[174:175], 0, s[10:11]
	v_lshl_add_u64 v[142:143], v[138:139], 0, s[100:101]
	s_waitcnt vmcnt(54)
	v_pk_fma_f32 v[28:29], s[82:83], v[28:29], v[222:223]
	v_pk_fma_f32 v[30:31], s[82:83], v[30:31], v[224:225]
	v_pk_fma_f32 v[20:21], s[82:83], v[20:21], v[226:227]
	v_pk_fma_f32 v[22:23], s[82:83], v[22:23], v[228:229]
	v_pk_fma_f32 v[12:13], s[82:83], v[12:13], v[230:231]
	v_pk_fma_f32 v[14:15], s[82:83], v[14:15], v[232:233]
	v_pk_fma_f32 v[4:5], s[82:83], v[4:5], v[234:235]
	v_pk_fma_f32 v[6:7], s[82:83], v[6:7], v[236:237]
	v_pk_fma_f32 v[24:25], s[82:83], v[24:25], v[238:239]
	v_pk_fma_f32 v[26:27], s[82:83], v[26:27], v[240:241]
	v_pk_fma_f32 v[16:17], s[82:83], v[16:17], v[242:243]
	v_pk_fma_f32 v[18:19], s[82:83], v[18:19], v[244:245]
	v_pk_fma_f32 v[8:9], s[82:83], v[8:9], v[246:247]
	v_pk_fma_f32 v[10:11], s[82:83], v[10:11], v[248:249]
	v_pk_fma_f32 v[0:1], s[82:83], v[0:1], v[250:251]
	v_pk_fma_f32 v[2:3], s[82:83], v[2:3], v[252:253]
	v_lshl_add_u64 v[174:175], v[140:141], 0, s[10:11]
	v_lshl_add_u64 v[138:139], v[142:143], 0, s[100:101]
	global_store_dwordx4 v[140:141], v[28:31], off
	v_cvt_pk_bf16_f32 v128, v28, v29
	v_cvt_pk_bf16_f32 v129, v30, v31
	v_mul_f32_e32 v148, v28, v28
	v_fmac_f32_e32 v148, v29, v29
	v_fmac_f32_e32 v148, v30, v30
	v_fmac_f32_e32 v148, v31, v31
	global_store_dwordx2 v[142:143], v[128:129], off
	global_store_dwordx4 v[140:141], v[20:23], off offset:64
	v_cvt_pk_bf16_f32 v130, v20, v21
	v_cvt_pk_bf16_f32 v131, v22, v23
	v_fmac_f32_e32 v148, v20, v20
	v_fmac_f32_e32 v148, v21, v21
	v_fmac_f32_e32 v148, v22, v22
	v_fmac_f32_e32 v148, v23, v23
	global_store_dwordx2 v[142:143], v[130:131], off offset:32
	global_store_dwordx4 v[140:141], v[12:15], off offset:512
	v_cvt_pk_bf16_f32 v132, v12, v13
	v_cvt_pk_bf16_f32 v133, v14, v15
	v_fmac_f32_e32 v148, v12, v12
	v_fmac_f32_e32 v148, v13, v13
	v_fmac_f32_e32 v148, v14, v14
	v_fmac_f32_e32 v148, v15, v15
	global_store_dwordx2 v[142:143], v[132:133], off offset:256
	global_store_dwordx4 v[140:141], v[4:7], off offset:576
	v_cvt_pk_bf16_f32 v134, v4, v5
	v_cvt_pk_bf16_f32 v135, v6, v7
	v_fmac_f32_e32 v148, v4, v4
	v_fmac_f32_e32 v148, v5, v5
	v_fmac_f32_e32 v148, v6, v6
	v_fmac_f32_e32 v148, v7, v7
	global_store_dwordx2 v[142:143], v[134:135], off offset:288
	global_store_dwordx4 v[174:175], v[24:27], off
	v_cvt_pk_bf16_f32 v128, v24, v25
	v_cvt_pk_bf16_f32 v129, v26, v27
	v_mul_f32_e32 v173, v24, v24
	v_fmac_f32_e32 v173, v25, v25
	v_fmac_f32_e32 v173, v26, v26
	v_fmac_f32_e32 v173, v27, v27
	global_store_dwordx2 v[138:139], v[128:129], off
	global_store_dwordx4 v[174:175], v[16:19], off offset:64
	v_cvt_pk_bf16_f32 v130, v16, v17
	v_cvt_pk_bf16_f32 v131, v18, v19
	v_fmac_f32_e32 v173, v16, v16
	v_fmac_f32_e32 v173, v17, v17
	v_fmac_f32_e32 v173, v18, v18
	v_fmac_f32_e32 v173, v19, v19
	global_store_dwordx2 v[138:139], v[130:131], off offset:32
	global_store_dwordx4 v[174:175], v[8:11], off offset:512
	v_cvt_pk_bf16_f32 v132, v8, v9
	v_cvt_pk_bf16_f32 v133, v10, v11
	v_fmac_f32_e32 v173, v8, v8
	v_fmac_f32_e32 v173, v9, v9
	v_fmac_f32_e32 v173, v10, v10
	v_fmac_f32_e32 v173, v11, v11
	global_store_dwordx2 v[138:139], v[132:133], off offset:256
	global_store_dwordx4 v[174:175], v[0:3], off offset:576
	v_cvt_pk_bf16_f32 v134, v0, v1
	v_cvt_pk_bf16_f32 v135, v2, v3
	v_fmac_f32_e32 v173, v0, v0
	v_fmac_f32_e32 v173, v1, v1
	v_fmac_f32_e32 v173, v2, v2
	v_fmac_f32_e32 v173, v3, v3
	global_store_dwordx2 v[138:139], v[134:135], off offset:288
	v_mov_b32_e32 v177, v148
	v_mov_b32_e32 v181, v173
	s_nop 1
	v_permlane16_swap_b32_e32 v148, v177
	v_permlane16_swap_b32_e32 v173, v181
	v_add_f32_e32 v148, v148, v177
	v_add_f32_e32 v173, v173, v181
	v_mov_b32_e32 v177, v148
	v_mov_b32_e32 v181, v173
	s_nop 1
	v_permlane32_swap_b32_e32 v148, v177
	v_permlane32_swap_b32_e32 v173, v181
	v_add_f32_e32 v148, v148, v177
	v_add_f32_e32 v173, v173, v181
	s_and_saveexec_b64 s[78:79], s[6:7]
	global_store_dword v[164:165], v148, off offset:2048
	global_store_dword v[164:165], v173, off offset:3072
	s_mov_b64 exec, s[78:79]
	s_branch .LBB0_514
